# grid barrier: all blocks poll TOP counter >= target, TOPGEN hop removed
# baseline (speedup 1.0000x reference)
.LBB0_37:
	s_or_b64 exec, exec, s[10:11]
	v_cvt_f32_u32_e32 v4, v2
	s_waitcnt vmcnt(0)
	v_readfirstlane_b32 s8, v3
	s_add_u32 s6, s88, 0xfc03400
	s_addc_u32 s7, s89, 0
	v_rcp_iflag_f32_e32 v4, v4
	v_add_u32_e32 v5, s8, v0
	v_mul_f32_e32 v3, 0x4f7ffffe, v4
	v_cvt_u32_f32_e32 v3, v3
	v_sub_u32_e32 v4, 0, v2
	v_mul_lo_u32 v0, v4, v3
	v_mul_hi_u32 v0, v3, v0
	v_add_u32_e32 v0, v3, v0
	v_mul_hi_u32 v0, v5, v0
	v_mul_lo_u32 v3, v0, v2
	v_sub_u32_e32 v3, v5, v3
	v_add_u32_e32 v4, 1, v0
	v_sub_u32_e32 v6, v3, v2
	v_cmp_ge_u32_e32 vcc, v3, v2
	s_nop 1
	v_cndmask_b32_e32 v0, v0, v4, vcc
	v_cndmask_b32_e32 v3, v3, v6, vcc
	v_add_u32_e32 v4, 1, v0
	v_cmp_ge_u32_e32 vcc, v3, v2
	v_add_u32_e32 v3, 1, v5
	s_nop 0
	v_cndmask_b32_e32 v0, v0, v4, vcc
	v_mul_lo_u32 v4, v2, v0
	v_add_u32_e32 v2, v4, v2
	v_cmp_ne_u32_e32 vcc, v3, v2
	s_and_saveexec_b64 s[8:9], vcc
	s_xor_b64 s[8:9], exec, s[8:9]
	s_cbranch_execz .LBB0_51
	s_waitcnt lgkmcnt(0)
	v_add_u32_e32 v0, 1, v0
	v_mul_lo_u32 v0, v0, v1
	v_mov_b32_e32 v1, 0
	global_load_dword v2, v1, s[6:7] sc1
	s_waitcnt vmcnt(0)
	v_cmp_lt_u32_e32 vcc, v2, v0
	s_and_saveexec_b64 s[10:11], vcc
	s_cbranch_execz .LBB0_50
	s_mov_b32 s22, 1
	s_mov_b64 s[12:13], 0
	s_branch .LBB0_41

.LBB0_45:
	global_load_dword v2, v1, s[6:7] sc1
	s_add_i32 s22, s22, 1
	s_mov_b64 s[18:19], -1
	s_waitcnt vmcnt(0)
	v_cmp_ge_u32_e32 vcc, v2, v0
	s_orn2_b64 s[16:17], vcc, exec
	s_branch .LBB0_40

.LBB0_54:
	s_or_b64 exec, exec, s[10:11]
	v_cvt_f32_u32_e32 v3, v1
	s_waitcnt vmcnt(0)
	v_readfirstlane_b32 s10, v2
	s_add_u32 s8, s88, 0xfc03400
	s_addc_u32 s9, s89, 0
	v_rcp_iflag_f32_e32 v3, v3
	v_add_u32_e32 v0, s10, v0
	s_mov_b64 s[12:13], 0
	v_mul_f32_e32 v2, 0x4f7ffffe, v3
	v_cvt_u32_f32_e32 v2, v2
	v_sub_u32_e32 v3, 0, v1
	v_mul_lo_u32 v3, v3, v2
	v_mul_hi_u32 v3, v2, v3
	v_add_u32_e32 v2, v2, v3
	v_mul_hi_u32 v2, v0, v2
	v_mul_lo_u32 v3, v2, v1
	v_sub_u32_e32 v3, v0, v3
	v_add_u32_e32 v4, 1, v2
	v_sub_u32_e32 v5, v3, v1
	v_cmp_ge_u32_e32 vcc, v3, v1
	v_add_u32_e32 v0, 1, v0
	s_nop 0
	v_cndmask_b32_e32 v2, v2, v4, vcc
	v_cndmask_b32_e32 v3, v3, v5, vcc
	v_add_u32_e32 v4, 1, v2
	v_cmp_ge_u32_e32 vcc, v3, v1
	s_nop 1
	v_cndmask_b32_e32 v2, v2, v4, vcc
	v_mul_lo_u32 v3, v1, v2
	v_add_u32_e32 v1, v3, v1
	v_cmp_ne_u32_e32 vcc, v0, v1
	v_mov_b32_e32 v2, v1
	s_and_saveexec_b64 s[10:11], vcc
	s_cbranch_execz .LBB0_66
	v_mov_b32_e32 v0, 0
	global_load_dword v1, v0, s[8:9] sc1
	s_mov_b64 s[14:15], 0
	s_waitcnt vmcnt(0)
	v_cmp_lt_u32_e32 vcc, v1, v2
	s_and_saveexec_b64 s[12:13], vcc
	s_cbranch_execz .LBB0_65
	s_mov_b32 s24, 1
	s_branch .LBB0_58

.LBB0_62:
	global_load_dword v1, v0, s[8:9] sc1
	s_add_i32 s24, s24, 1
	s_mov_b64 s[18:19], -1
	s_waitcnt vmcnt(0)
	v_cmp_ge_u32_e32 vcc, v1, v2
	s_orn2_b64 s[22:23], vcc, exec
	s_branch .LBB0_57

.LBB0_152:
	s_or_b64 exec, exec, s[12:13]
	v_cvt_f32_u32_e32 v4, v2
	s_waitcnt vmcnt(0)
	v_readfirstlane_b32 s10, v3
	s_add_u32 s8, s88, 0xfc03400
	s_addc_u32 s9, s89, 0
	v_rcp_iflag_f32_e32 v4, v4
	v_add_u32_e32 v5, s10, v0
	v_mul_f32_e32 v3, 0x4f7ffffe, v4
	v_cvt_u32_f32_e32 v3, v3
	v_sub_u32_e32 v4, 0, v2
	v_mul_lo_u32 v0, v4, v3
	v_mul_hi_u32 v0, v3, v0
	v_add_u32_e32 v0, v3, v0
	v_mul_hi_u32 v0, v5, v0
	v_mul_lo_u32 v3, v0, v2
	v_sub_u32_e32 v3, v5, v3
	v_add_u32_e32 v4, 1, v0
	v_cmp_ge_u32_e32 vcc, v3, v2
	s_nop 1
	v_cndmask_b32_e32 v0, v0, v4, vcc
	v_sub_u32_e32 v4, v3, v2
	v_cndmask_b32_e32 v3, v3, v4, vcc
	v_add_u32_e32 v4, 1, v0
	v_cmp_ge_u32_e32 vcc, v3, v2
	v_add_u32_e32 v3, 1, v5
	s_nop 0
	v_cndmask_b32_e32 v0, v0, v4, vcc
	v_mul_lo_u32 v4, v2, v0
	v_add_u32_e32 v2, v4, v2
	v_cmp_ne_u32_e32 vcc, v3, v2
	s_and_saveexec_b64 s[10:11], vcc
	s_xor_b64 s[10:11], exec, s[10:11]
	s_cbranch_execz .LBB0_166
	s_waitcnt lgkmcnt(0)
	v_add_u32_e32 v0, 1, v0
	v_mul_lo_u32 v0, v0, v1
	v_mov_b32_e32 v1, 0
	global_load_dword v2, v1, s[8:9] sc1
	s_waitcnt vmcnt(0)
	v_cmp_lt_u32_e32 vcc, v2, v0
	s_and_saveexec_b64 s[12:13], vcc
	s_cbranch_execz .LBB0_165
	s_mov_b32 s24, 1
	s_mov_b64 s[14:15], 0
	s_branch .LBB0_156

.LBB0_160:
	global_load_dword v2, v1, s[8:9] sc1
	s_add_i32 s24, s24, 1
	s_mov_b64 s[20:21], -1
	s_waitcnt vmcnt(0)
	v_cmp_ge_u32_e32 vcc, v2, v0
	s_orn2_b64 s[18:19], vcc, exec
	s_branch .LBB0_155

.LBB0_169:
	s_or_b64 exec, exec, s[12:13]
	v_cvt_f32_u32_e32 v3, v1
	s_waitcnt vmcnt(0)
	v_readfirstlane_b32 s12, v2
	s_add_u32 s10, s88, 0xfc03400
	s_addc_u32 s11, s89, 0
	v_rcp_iflag_f32_e32 v3, v3
	v_add_u32_e32 v0, s12, v0
	s_mov_b64 s[14:15], 0
	v_mul_f32_e32 v2, 0x4f7ffffe, v3
	v_cvt_u32_f32_e32 v2, v2
	v_sub_u32_e32 v3, 0, v1
	v_mul_lo_u32 v3, v3, v2
	v_mul_hi_u32 v3, v2, v3
	v_add_u32_e32 v2, v2, v3
	v_mul_hi_u32 v2, v0, v2
	v_mul_lo_u32 v3, v2, v1
	v_sub_u32_e32 v3, v0, v3
	v_add_u32_e32 v4, 1, v2
	v_cmp_ge_u32_e32 vcc, v3, v1
	v_add_u32_e32 v0, 1, v0
	s_nop 0
	v_cndmask_b32_e32 v2, v2, v4, vcc
	v_sub_u32_e32 v4, v3, v1
	v_cndmask_b32_e32 v3, v3, v4, vcc
	v_add_u32_e32 v4, 1, v2
	v_cmp_ge_u32_e32 vcc, v3, v1
	s_nop 1
	v_cndmask_b32_e32 v2, v2, v4, vcc
	v_mul_lo_u32 v3, v1, v2
	v_add_u32_e32 v1, v3, v1
	v_cmp_ne_u32_e32 vcc, v0, v1
	v_mov_b32_e32 v2, v1
	s_and_saveexec_b64 s[12:13], vcc
	s_cbranch_execz .LBB0_181
	v_mov_b32_e32 v0, 0
	global_load_dword v1, v0, s[10:11] sc1
	s_mov_b64 s[16:17], 0
	s_waitcnt vmcnt(0)
	v_cmp_lt_u32_e32 vcc, v1, v2
	s_and_saveexec_b64 s[14:15], vcc
	s_cbranch_execz .LBB0_180
	s_mov_b32 s26, 1
	s_branch .LBB0_173

.LBB0_177:
	global_load_dword v1, v0, s[10:11] sc1
	s_add_i32 s26, s26, 1
	s_mov_b64 s[20:21], -1
	s_waitcnt vmcnt(0)
	v_cmp_ge_u32_e32 vcc, v1, v2
	s_orn2_b64 s[24:25], vcc, exec
	s_branch .LBB0_172

.LBB0_215:
	s_or_b64 exec, exec, s[12:13]
	v_cvt_f32_u32_e32 v4, v2
	s_waitcnt vmcnt(0)
	v_readfirstlane_b32 s8, v3
	s_add_u32 s6, s88, 0xfc03400
	s_addc_u32 s7, s89, 0
	v_rcp_iflag_f32_e32 v4, v4
	v_add_u32_e32 v5, s8, v0
	v_mul_f32_e32 v3, 0x4f7ffffe, v4
	v_cvt_u32_f32_e32 v3, v3
	v_sub_u32_e32 v4, 0, v2
	v_mul_lo_u32 v0, v4, v3
	v_mul_hi_u32 v0, v3, v0
	v_add_u32_e32 v0, v3, v0
	v_mul_hi_u32 v0, v5, v0
	v_mul_lo_u32 v3, v0, v2
	v_sub_u32_e32 v3, v5, v3
	v_add_u32_e32 v4, 1, v0
	v_cmp_ge_u32_e32 vcc, v3, v2
	s_nop 1
	v_cndmask_b32_e32 v0, v0, v4, vcc
	v_sub_u32_e32 v4, v3, v2
	v_cndmask_b32_e32 v3, v3, v4, vcc
	v_add_u32_e32 v4, 1, v0
	v_cmp_ge_u32_e32 vcc, v3, v2
	v_add_u32_e32 v3, 1, v5
	s_nop 0
	v_cndmask_b32_e32 v0, v0, v4, vcc
	v_mul_lo_u32 v4, v2, v0
	v_add_u32_e32 v2, v4, v2
	v_cmp_ne_u32_e32 vcc, v3, v2
	s_and_saveexec_b64 s[8:9], vcc
	s_xor_b64 s[8:9], exec, s[8:9]
	s_cbranch_execz .LBB0_229
	s_waitcnt lgkmcnt(0)
	v_add_u32_e32 v0, 1, v0
	v_mul_lo_u32 v0, v0, v1
	v_mov_b32_e32 v1, 0
	global_load_dword v2, v1, s[6:7] sc1
	s_waitcnt vmcnt(0)
	v_cmp_lt_u32_e32 vcc, v2, v0
	s_and_saveexec_b64 s[12:13], vcc
	s_cbranch_execz .LBB0_228
	s_mov_b32 s24, 1
	s_mov_b64 s[14:15], 0
	s_branch .LBB0_219

.LBB0_223:
	global_load_dword v2, v1, s[6:7] sc1
	s_add_i32 s24, s24, 1
	s_mov_b64 s[20:21], -1
	s_waitcnt vmcnt(0)
	v_cmp_ge_u32_e32 vcc, v2, v0
	s_orn2_b64 s[18:19], vcc, exec
	s_branch .LBB0_218

.LBB0_232:
	s_or_b64 exec, exec, s[12:13]
	v_cvt_f32_u32_e32 v3, v1
	s_waitcnt vmcnt(0)
	v_readfirstlane_b32 s12, v2
	s_add_u32 s8, s88, 0xfc03400
	s_addc_u32 s9, s89, 0
	v_rcp_iflag_f32_e32 v3, v3
	v_add_u32_e32 v0, s12, v0
	s_mov_b64 s[14:15], 0
	v_mul_f32_e32 v2, 0x4f7ffffe, v3
	v_cvt_u32_f32_e32 v2, v2
	v_sub_u32_e32 v3, 0, v1
	v_mul_lo_u32 v3, v3, v2
	v_mul_hi_u32 v3, v2, v3
	v_add_u32_e32 v2, v2, v3
	v_mul_hi_u32 v2, v0, v2
	v_mul_lo_u32 v3, v2, v1
	v_sub_u32_e32 v3, v0, v3
	v_add_u32_e32 v4, 1, v2
	v_cmp_ge_u32_e32 vcc, v3, v1
	v_add_u32_e32 v0, 1, v0
	s_nop 0
	v_cndmask_b32_e32 v2, v2, v4, vcc
	v_sub_u32_e32 v4, v3, v1
	v_cndmask_b32_e32 v3, v3, v4, vcc
	v_add_u32_e32 v4, 1, v2
	v_cmp_ge_u32_e32 vcc, v3, v1
	s_nop 1
	v_cndmask_b32_e32 v2, v2, v4, vcc
	v_mul_lo_u32 v3, v1, v2
	v_add_u32_e32 v1, v3, v1
	v_cmp_ne_u32_e32 vcc, v0, v1
	v_mov_b32_e32 v2, v1
	s_and_saveexec_b64 s[12:13], vcc
	s_cbranch_execz .LBB0_244
	v_mov_b32_e32 v0, 0
	global_load_dword v1, v0, s[8:9] sc1
	s_mov_b64 s[16:17], 0
	s_waitcnt vmcnt(0)
	v_cmp_lt_u32_e32 vcc, v1, v2
	s_and_saveexec_b64 s[14:15], vcc
	s_cbranch_execz .LBB0_243
	s_mov_b32 s26, 1
	s_branch .LBB0_236

.LBB0_240:
	global_load_dword v1, v0, s[8:9] sc1
	s_add_i32 s26, s26, 1
	s_mov_b64 s[20:21], -1
	s_waitcnt vmcnt(0)
	v_cmp_ge_u32_e32 vcc, v1, v2
	s_orn2_b64 s[24:25], vcc, exec
	s_branch .LBB0_235

.LBB0_368:
	s_or_b64 exec, exec, s[6:7]
	v_cvt_f32_u32_e32 v4, v2
	s_waitcnt vmcnt(0)
	v_readfirstlane_b32 s4, v3
	s_add_u32 s2, s88, 0xfc03400
	s_addc_u32 s3, s89, 0
	v_rcp_iflag_f32_e32 v4, v4
	v_add_u32_e32 v5, s4, v1
	v_mul_f32_e32 v3, 0x4f7ffffe, v4
	v_cvt_u32_f32_e32 v3, v3
	v_sub_u32_e32 v4, 0, v2
	v_mul_lo_u32 v1, v4, v3
	v_mul_hi_u32 v1, v3, v1
	v_add_u32_e32 v1, v3, v1
	v_mul_hi_u32 v1, v5, v1
	v_mul_lo_u32 v3, v1, v2
	v_sub_u32_e32 v3, v5, v3
	v_add_u32_e32 v4, 1, v1
	v_cmp_ge_u32_e32 vcc, v3, v2
	s_nop 1
	v_cndmask_b32_e32 v1, v1, v4, vcc
	v_sub_u32_e32 v4, v3, v2
	v_cndmask_b32_e32 v3, v3, v4, vcc
	v_add_u32_e32 v4, 1, v1
	v_cmp_ge_u32_e32 vcc, v3, v2
	v_add_u32_e32 v3, 1, v5
	s_nop 0
	v_cndmask_b32_e32 v1, v1, v4, vcc
	v_mul_lo_u32 v4, v2, v1
	v_add_u32_e32 v2, v4, v2
	v_cmp_ne_u32_e32 vcc, v3, v2
	s_and_saveexec_b64 s[4:5], vcc
	s_xor_b64 s[4:5], exec, s[4:5]
	s_cbranch_execz .LBB0_382
	s_waitcnt lgkmcnt(0)
	v_add_u32_e32 v1, 1, v1
	v_mul_lo_u32 v1, v1, v0
	v_mov_b32_e32 v0, 0
	global_load_dword v2, v0, s[2:3] sc1
	s_waitcnt vmcnt(0)
	v_cmp_lt_u32_e32 vcc, v2, v1
	s_and_saveexec_b64 s[6:7], vcc
	s_cbranch_execz .LBB0_381
	s_mov_b32 s20, 1
	s_mov_b64 s[10:11], 0
	s_branch .LBB0_372

.LBB0_376:
	global_load_dword v2, v0, s[2:3] sc1
	s_add_i32 s20, s20, 1
	s_mov_b64 s[16:17], -1
	s_waitcnt vmcnt(0)
	v_cmp_ge_u32_e32 vcc, v2, v1
	s_orn2_b64 s[14:15], vcc, exec
	s_branch .LBB0_371

.LBB0_385:
	s_or_b64 exec, exec, s[6:7]
	v_cvt_f32_u32_e32 v3, v0
	s_waitcnt vmcnt(0)
	v_readfirstlane_b32 s6, v2
	s_add_u32 s4, s88, 0xfc03400
	s_addc_u32 s5, s89, 0
	v_rcp_iflag_f32_e32 v3, v3
	v_add_u32_e32 v1, s6, v1
	s_mov_b64 s[10:11], 0
	v_mul_f32_e32 v2, 0x4f7ffffe, v3
	v_cvt_u32_f32_e32 v2, v2
	v_sub_u32_e32 v3, 0, v0
	v_mul_lo_u32 v3, v3, v2
	v_mul_hi_u32 v3, v2, v3
	v_add_u32_e32 v2, v2, v3
	v_mul_hi_u32 v2, v1, v2
	v_mul_lo_u32 v3, v2, v0
	v_sub_u32_e32 v3, v1, v3
	v_add_u32_e32 v4, 1, v2
	v_cmp_ge_u32_e32 vcc, v3, v0
	v_add_u32_e32 v1, 1, v1
	s_nop 0
	v_cndmask_b32_e32 v2, v2, v4, vcc
	v_sub_u32_e32 v4, v3, v0
	v_cndmask_b32_e32 v3, v3, v4, vcc
	v_add_u32_e32 v4, 1, v2
	v_cmp_ge_u32_e32 vcc, v3, v0
	s_nop 1
	v_cndmask_b32_e32 v2, v2, v4, vcc
	v_mul_lo_u32 v3, v0, v2
	v_add_u32_e32 v0, v3, v0
	v_cmp_ne_u32_e32 vcc, v1, v0
	v_mov_b32_e32 v2, v0
	s_and_saveexec_b64 s[6:7], vcc
	s_cbranch_execz .LBB0_397
	v_mov_b32_e32 v0, 0
	global_load_dword v1, v0, s[4:5] sc1
	s_mov_b64 s[12:13], 0
	s_waitcnt vmcnt(0)
	v_cmp_lt_u32_e32 vcc, v1, v2
	s_and_saveexec_b64 s[10:11], vcc
	s_cbranch_execz .LBB0_396
	s_mov_b32 s22, 1
	s_branch .LBB0_389

.LBB0_393:
	global_load_dword v1, v0, s[4:5] sc1
	s_add_i32 s22, s22, 1
	s_mov_b64 s[16:17], -1
	s_waitcnt vmcnt(0)
	v_cmp_ge_u32_e32 vcc, v1, v2
	s_orn2_b64 s[20:21], vcc, exec
	s_branch .LBB0_388

.LBB0_718:
	s_or_b64 exec, exec, s[10:11]
	v_cvt_f32_u32_e32 v4, v2
	s_waitcnt vmcnt(0)
	v_readfirstlane_b32 s8, v3
	s_add_u32 s6, s88, 0xfc03400
	s_addc_u32 s7, s89, 0
	v_rcp_iflag_f32_e32 v4, v4
	v_add_u32_e32 v5, s8, v0
	v_mul_f32_e32 v3, 0x4f7ffffe, v4
	v_cvt_u32_f32_e32 v3, v3
	v_sub_u32_e32 v4, 0, v2
	v_mul_lo_u32 v0, v4, v3
	v_mul_hi_u32 v0, v3, v0
	v_add_u32_e32 v0, v3, v0
	v_mul_hi_u32 v0, v5, v0
	v_mul_lo_u32 v3, v0, v2
	v_sub_u32_e32 v3, v5, v3
	v_add_u32_e32 v4, 1, v0
	v_cmp_ge_u32_e32 vcc, v3, v2
	s_nop 1
	v_cndmask_b32_e32 v0, v0, v4, vcc
	v_sub_u32_e32 v4, v3, v2
	v_cndmask_b32_e32 v3, v3, v4, vcc
	v_add_u32_e32 v4, 1, v0
	v_cmp_ge_u32_e32 vcc, v3, v2
	v_add_u32_e32 v3, 1, v5
	s_nop 0
	v_cndmask_b32_e32 v0, v0, v4, vcc
	v_mul_lo_u32 v4, v2, v0
	v_add_u32_e32 v2, v4, v2
	v_cmp_ne_u32_e32 vcc, v3, v2
	s_and_saveexec_b64 s[8:9], vcc
	s_xor_b64 s[8:9], exec, s[8:9]
	s_cbranch_execz .LBB0_732
	s_waitcnt lgkmcnt(0)
	v_add_u32_e32 v0, 1, v0
	v_mul_lo_u32 v0, v0, v1
	v_mov_b32_e32 v1, 0
	global_load_dword v2, v1, s[6:7] sc1
	s_waitcnt vmcnt(0)
	v_cmp_lt_u32_e32 vcc, v2, v0
	s_and_saveexec_b64 s[10:11], vcc
	s_cbranch_execz .LBB0_731
	s_mov_b32 s22, 1
	s_mov_b64 s[12:13], 0
	s_branch .LBB0_722

.LBB0_735:
	s_or_b64 exec, exec, s[10:11]
	v_cvt_f32_u32_e32 v3, v1
	s_waitcnt vmcnt(0)
	v_readfirstlane_b32 s10, v2
	s_add_u32 s8, s88, 0xfc03400
	s_addc_u32 s9, s89, 0
	v_rcp_iflag_f32_e32 v3, v3
	v_add_u32_e32 v0, s10, v0
	s_mov_b64 s[12:13], 0
	v_mul_f32_e32 v2, 0x4f7ffffe, v3
	v_cvt_u32_f32_e32 v2, v2
	v_sub_u32_e32 v3, 0, v1
	v_mul_lo_u32 v3, v3, v2
	v_mul_hi_u32 v3, v2, v3
	v_add_u32_e32 v2, v2, v3
	v_mul_hi_u32 v2, v0, v2
	v_mul_lo_u32 v3, v2, v1
	v_sub_u32_e32 v3, v0, v3
	v_add_u32_e32 v4, 1, v2
	v_cmp_ge_u32_e32 vcc, v3, v1
	v_add_u32_e32 v0, 1, v0
	s_nop 0
	v_cndmask_b32_e32 v2, v2, v4, vcc
	v_sub_u32_e32 v4, v3, v1
	v_cndmask_b32_e32 v3, v3, v4, vcc
	v_add_u32_e32 v4, 1, v2
	v_cmp_ge_u32_e32 vcc, v3, v1
	s_nop 1
	v_cndmask_b32_e32 v2, v2, v4, vcc
	v_mul_lo_u32 v3, v1, v2
	v_add_u32_e32 v1, v3, v1
	v_cmp_ne_u32_e32 vcc, v0, v1
	v_mov_b32_e32 v2, v1
	s_and_saveexec_b64 s[10:11], vcc
	s_cbranch_execz .LBB0_747
	v_mov_b32_e32 v0, 0
	global_load_dword v1, v0, s[8:9] sc1
	s_mov_b64 s[14:15], 0
	s_waitcnt vmcnt(0)
	v_cmp_lt_u32_e32 vcc, v1, v2
	s_and_saveexec_b64 s[12:13], vcc
	s_cbranch_execz .LBB0_746
	s_mov_b32 s24, 1
	s_branch .LBB0_739

.LBB0_1200:
	s_or_b64 exec, exec, s[8:9]
	v_cvt_f32_u32_e32 v4, v2
	s_waitcnt vmcnt(0)
	v_readfirstlane_b32 s6, v3
	s_add_u32 s4, s88, 0xfc03400
	s_addc_u32 s5, s89, 0
	v_rcp_iflag_f32_e32 v4, v4
	v_add_u32_e32 v5, s6, v0
	v_mul_f32_e32 v3, 0x4f7ffffe, v4
	v_cvt_u32_f32_e32 v3, v3
	v_sub_u32_e32 v4, 0, v2
	v_mul_lo_u32 v0, v4, v3
	v_mul_hi_u32 v0, v3, v0
	v_add_u32_e32 v0, v3, v0
	v_mul_hi_u32 v0, v5, v0
	v_mul_lo_u32 v3, v0, v2
	v_sub_u32_e32 v3, v5, v3
	v_add_u32_e32 v4, 1, v0
	v_cmp_ge_u32_e32 vcc, v3, v2
	s_nop 1
	v_cndmask_b32_e32 v0, v0, v4, vcc
	v_sub_u32_e32 v4, v3, v2
	v_cndmask_b32_e32 v3, v3, v4, vcc
	v_add_u32_e32 v4, 1, v0
	v_cmp_ge_u32_e32 vcc, v3, v2
	v_add_u32_e32 v3, 1, v5
	s_nop 0
	v_cndmask_b32_e32 v0, v0, v4, vcc
	v_mul_lo_u32 v4, v2, v0
	v_add_u32_e32 v2, v4, v2
	v_cmp_ne_u32_e32 vcc, v3, v2
	s_and_saveexec_b64 s[6:7], vcc
	s_xor_b64 s[6:7], exec, s[6:7]
	s_cbranch_execz .LBB0_1214
	s_waitcnt lgkmcnt(0)
	v_add_u32_e32 v0, 1, v0
	v_mul_lo_u32 v0, v0, v1
	v_mov_b32_e32 v1, 0
	global_load_dword v2, v1, s[4:5] sc1
	s_waitcnt vmcnt(0)
	v_cmp_lt_u32_e32 vcc, v2, v0
	s_and_saveexec_b64 s[8:9], vcc
	s_cbranch_execz .LBB0_1213
	s_mov_b32 s20, 1
	s_mov_b64 s[10:11], 0
	s_branch .LBB0_1204

.LBB0_1208:
	global_load_dword v2, v1, s[4:5] sc1
	s_add_i32 s20, s20, 1
	s_mov_b64 s[16:17], -1
	s_waitcnt vmcnt(0)
	v_cmp_ge_u32_e32 vcc, v2, v0
	s_orn2_b64 s[14:15], vcc, exec
	s_branch .LBB0_1203

.LBB0_1217:
	s_or_b64 exec, exec, s[8:9]
	v_cvt_f32_u32_e32 v3, v1
	s_waitcnt vmcnt(0)
	v_readfirstlane_b32 s8, v2
	s_add_u32 s6, s88, 0xfc03400
	s_addc_u32 s7, s89, 0
	v_rcp_iflag_f32_e32 v3, v3
	v_add_u32_e32 v0, s8, v0
	s_mov_b64 s[10:11], 0
	v_mul_f32_e32 v2, 0x4f7ffffe, v3
	v_cvt_u32_f32_e32 v2, v2
	v_sub_u32_e32 v3, 0, v1
	v_mul_lo_u32 v3, v3, v2
	v_mul_hi_u32 v3, v2, v3
	v_add_u32_e32 v2, v2, v3
	v_mul_hi_u32 v2, v0, v2
	v_mul_lo_u32 v3, v2, v1
	v_sub_u32_e32 v3, v0, v3
	v_add_u32_e32 v4, 1, v2
	v_cmp_ge_u32_e32 vcc, v3, v1
	v_add_u32_e32 v0, 1, v0
	s_nop 0
	v_cndmask_b32_e32 v2, v2, v4, vcc
	v_sub_u32_e32 v4, v3, v1
	v_cndmask_b32_e32 v3, v3, v4, vcc
	v_add_u32_e32 v4, 1, v2
	v_cmp_ge_u32_e32 vcc, v3, v1
	s_nop 1
	v_cndmask_b32_e32 v2, v2, v4, vcc
	v_mul_lo_u32 v3, v1, v2
	v_add_u32_e32 v1, v3, v1
	v_cmp_ne_u32_e32 vcc, v0, v1
	v_mov_b32_e32 v2, v1
	s_and_saveexec_b64 s[8:9], vcc
	s_cbranch_execz .LBB0_1229
	v_mov_b32_e32 v0, 0
	global_load_dword v1, v0, s[6:7] sc1
	s_mov_b64 s[12:13], 0
	s_waitcnt vmcnt(0)
	v_cmp_lt_u32_e32 vcc, v1, v2
	s_and_saveexec_b64 s[10:11], vcc
	s_cbranch_execz .LBB0_1228
	s_mov_b32 s22, 1
	s_branch .LBB0_1221

.LBB0_1225:
	global_load_dword v1, v0, s[6:7] sc1
	s_add_i32 s22, s22, 1
	s_mov_b64 s[16:17], -1
	s_waitcnt vmcnt(0)
	v_cmp_ge_u32_e32 vcc, v1, v2
	s_orn2_b64 s[20:21], vcc, exec
	s_branch .LBB0_1220

.LBB0_1574:
	s_cmp_lt_i32 s90, 13
	s_cselect_b64 s[20:21], -1, 0
	s_cmp_gt_i32 s91, 12
	s_cselect_b64 s[0:1], -1, 0
	s_and_b64 s[0:1], s[20:21], s[0:1]
	s_andn2_b64 vcc, exec, s[0:1]
	s_cbranch_vccnz .LBB0_1712
	s_mov_b64 s[0:1], s[92:93]
	s_mul_i32 s18, s1, s0
	s_add_u32 s0, s88, 0xfc00200
	s_addc_u32 s1, s89, 0
	s_add_u32 s38, s88, 0xfc00400
	v_writelane_b32 v254, s0, 27
	s_addc_u32 s39, s89, 0
	s_nop 0
	v_writelane_b32 v254, s1, 28
	s_add_u32 s0, s88, 0xfc00500
	s_addc_u32 s1, s89, 0
	v_writelane_b32 v253, s0, 7
	s_nop 1
	v_writelane_b32 v253, s1, 8
	s_add_u32 s0, s88, 0xfc00600
	s_addc_u32 s1, s89, 0
	s_add_u32 s60, s88, 0xfc00700
	s_addc_u32 s61, s89, 0
	s_add_u32 s62, s88, 0xfc00800
	s_addc_u32 s63, s89, 0
	s_add_u32 s64, s88, 0xfc00900
	s_addc_u32 s65, s89, 0
	s_add_u32 s66, s88, 0xfc00a00
	s_addc_u32 s67, s89, 0
	s_add_u32 s68, s88, 0xfc00b00
	s_addc_u32 s69, s89, 0
	s_add_u32 s72, s88, 0xfc00c00
	s_addc_u32 s73, s89, 0
	s_add_u32 s74, s88, 0xfc00d00
	s_addc_u32 s75, s89, 0
	s_add_u32 s76, s88, 0xfc00e00
	s_addc_u32 s77, s89, 0
	s_add_u32 s78, s88, 0xfc00f00
	s_addc_u32 s79, s89, 0
	s_add_u32 s80, s88, 0xfc01000
	s_addc_u32 s81, s89, 0
	s_add_u32 s82, s88, 0xfc01100
	s_addc_u32 s83, s89, 0
	s_add_u32 s84, s88, 0xfc01200
	s_addc_u32 s85, s89, 0
	v_writelane_b32 v254, s0, 9
	s_add_u32 s86, s88, 0xfc01300
	s_addc_u32 s87, s89, 0
	v_writelane_b32 v254, s1, 10
	v_readlane_b32 s0, v253, 5
	s_cmp_eq_u32 s0, 15
	s_cselect_b64 s[26:27], -1, 0
	s_cmp_eq_u32 s0, 14
	s_cselect_b64 s[28:29], -1, 0
	s_cmp_eq_u32 s0, 13
	s_cselect_b64 s[30:31], -1, 0
	s_cmp_eq_u32 s0, 12
	s_cselect_b64 s[34:35], -1, 0
	s_cmp_eq_u32 s0, 11
	s_cselect_b64 s[42:43], -1, 0
	s_cmp_eq_u32 s0, 10
	s_cselect_b64 s[2:3], -1, 0
	v_writelane_b32 v254, s2, 7
	s_cmp_eq_u32 s0, 9
	s_nop 0
	v_writelane_b32 v254, s3, 8
	s_cselect_b64 s[2:3], -1, 0
	v_writelane_b32 v254, s2, 31
	s_cmp_eq_u32 s0, 8
	s_nop 0
	v_writelane_b32 v254, s3, 32
	s_cselect_b64 s[2:3], -1, 0
	v_writelane_b32 v254, s2, 33
	s_cmp_eq_u32 s0, 7
	s_nop 0
	v_writelane_b32 v254, s3, 34
	s_cselect_b64 s[2:3], -1, 0
	v_writelane_b32 v254, s2, 35
	s_cmp_eq_u32 s0, 6
	s_nop 0
	v_writelane_b32 v254, s3, 36
	s_cselect_b64 s[2:3], -1, 0
	v_writelane_b32 v254, s2, 37
	s_cmp_eq_u32 s0, 5
	s_nop 0
	v_writelane_b32 v254, s3, 38
	s_cselect_b64 s[2:3], -1, 0
	v_writelane_b32 v254, s2, 39
	s_cmp_eq_u32 s0, 4
	s_nop 0
	v_writelane_b32 v254, s3, 40
	s_cselect_b64 s[2:3], -1, 0
	v_writelane_b32 v254, s2, 41
	s_cmp_eq_u32 s0, 3
	s_nop 0
	v_writelane_b32 v254, s3, 42
	s_cselect_b64 s[2:3], -1, 0
	v_writelane_b32 v254, s2, 43
	s_cmp_eq_u32 s0, 2
	s_nop 0
	v_writelane_b32 v254, s3, 44
	s_cselect_b64 s[2:3], -1, 0
	v_writelane_b32 v254, s2, 45
	s_cmp_eq_u32 s0, 1
	s_nop 0
	v_writelane_b32 v254, s3, 46
	s_cselect_b64 s[2:3], -1, 0
	v_writelane_b32 v254, s2, 47
	s_cmp_eq_u32 s0, 0
	s_nop 0
	v_writelane_b32 v254, s3, 48
	s_cselect_b64 s[2:3], -1, 0
	v_writelane_b32 v254, s2, 49
	s_lshl_b32 s0, s0, 8
	s_nop 0
	v_writelane_b32 v254, s3, 50
	v_readlane_b32 s2, v253, 3
	v_readlane_b32 s3, v253, 4
	s_add_u32 s0, s2, s0
	s_addc_u32 s1, s3, 0
	s_add_u32 s10, s0, 0x1400
	s_addc_u32 s11, s1, 0
	s_add_u32 s0, s88, 0xfc03400
	s_addc_u32 s1, s89, 0
	s_add_u32 s22, s88, 0xfc03400
	v_writelane_b32 v254, s0, 29
	s_addc_u32 s23, s89, 0
	s_nop 0
	v_writelane_b32 v254, s1, 30
	s_add_u32 s0, s88, 0xfc03400
	s_addc_u32 s1, s89, 0
	v_writelane_b32 v254, s0, 25
	s_andn2_b64 vcc, exec, s[36:37]
	s_nop 0
	v_writelane_b32 v254, s1, 26
	v_readlane_b32 s0, v253, 2
	s_mul_i32 s18, s18, s0
	s_cbranch_vccnz .LBB0_1629
	s_waitcnt vmcnt(0)
	s_waitcnt lgkmcnt(0)
	s_barrier
	s_mov_b64 s[0:1], exec
	v_readlane_b32 s2, v253, 0
	v_readlane_b32 s3, v253, 1
	s_and_b64 s[2:3], s[0:1], s[2:3]
	s_mov_b64 exec, s[2:3]
	s_cbranch_execz .LBB0_1628
	v_mov_b32_e32 v16, 0
	s_waitcnt vmcnt(0) expcnt(0) lgkmcnt(0)
	ds_read_b32 v2, v16
	ds_read_b32 v0, v16 offset:4
	s_waitcnt lgkmcnt(1)
	v_cmp_ne_u32_e32 vcc, 0, v2
	s_cbranch_vccnz .LBB0_1592
	s_mov_b32 s8, 1
	s_branch .LBB0_1580

.LBB0_1594:
	s_or_b64 exec, exec, s[2:3]
	v_cvt_f32_u32_e32 v4, v2
	s_waitcnt vmcnt(0)
	v_readfirstlane_b32 s2, v3
	v_sub_u32_e32 v3, 0, v2
	v_rcp_iflag_f32_e32 v4, v4
	v_add_u32_e32 v5, s2, v1
	v_mul_f32_e32 v4, 0x4f7ffffe, v4
	v_cvt_u32_f32_e32 v4, v4
	v_mul_lo_u32 v1, v3, v4
	v_mul_hi_u32 v1, v4, v1
	v_add_u32_e32 v1, v4, v1
	v_mul_hi_u32 v1, v5, v1
	v_mul_lo_u32 v3, v1, v2
	v_sub_u32_e32 v3, v5, v3
	v_add_u32_e32 v4, 1, v1
	v_cmp_ge_u32_e32 vcc, v3, v2
	s_nop 1
	v_cndmask_b32_e32 v1, v1, v4, vcc
	v_sub_u32_e32 v4, v3, v2
	v_cndmask_b32_e32 v3, v3, v4, vcc
	v_add_u32_e32 v4, 1, v1
	v_cmp_ge_u32_e32 vcc, v3, v2
	v_add_u32_e32 v3, 1, v5
	s_nop 0
	v_cndmask_b32_e32 v1, v1, v4, vcc
	v_mul_lo_u32 v4, v2, v1
	v_add_u32_e32 v2, v4, v2
	v_cmp_ne_u32_e32 vcc, v3, v2
	s_and_saveexec_b64 s[2:3], vcc
	s_xor_b64 s[2:3], exec, s[2:3]
	s_cbranch_execz .LBB0_1608
	v_readlane_b32 s4, v254, 29
	s_waitcnt lgkmcnt(0)
	v_add_u32_e32 v1, 1, v1
	v_mul_lo_u32 v1, v1, v0
	v_mov_b32_e32 v0, 0
	v_readlane_b32 s5, v254, 30
	s_nop 4
	global_load_dword v2, v0, s[4:5] sc1
	s_waitcnt vmcnt(0)
	v_cmp_lt_u32_e32 vcc, v2, v1
	s_and_saveexec_b64 s[4:5], vcc
	s_cbranch_execz .LBB0_1607
	s_mov_b64 s[24:25], s[10:11]
	s_mov_b32 s16, 1
	s_mov_b64 s[6:7], 0
	s_branch .LBB0_1598

.LBB0_1602:
	v_readlane_b32 s10, v254, 29
	v_readlane_b32 s11, v254, 30
	s_add_i32 s16, s16, 1
	s_mov_b64 s[12:13], -1
	s_nop 2
	global_load_dword v2, v0, s[10:11] sc1
	s_waitcnt vmcnt(0)
	v_cmp_ge_u32_e32 vcc, v2, v1
	s_orn2_b64 s[10:11], vcc, exec
	s_branch .LBB0_1597

.LBB0_1611:
	s_or_b64 exec, exec, s[4:5]
	s_waitcnt vmcnt(0)
	v_readfirstlane_b32 s2, v2
	v_cvt_f32_u32_e32 v2, v0
	v_sub_u32_e32 v3, 0, v0
	v_add_u32_e32 v1, s2, v1
	v_readlane_b32 s2, v254, 25
	v_rcp_iflag_f32_e32 v2, v2
	v_readlane_b32 s3, v254, 26
	s_mov_b64 s[4:5], 0
	v_mul_f32_e32 v2, 0x4f7ffffe, v2
	v_cvt_u32_f32_e32 v2, v2
	v_mul_lo_u32 v3, v3, v2
	v_mul_hi_u32 v3, v2, v3
	v_add_u32_e32 v2, v2, v3
	v_mul_hi_u32 v2, v1, v2
	v_mul_lo_u32 v3, v2, v0
	v_sub_u32_e32 v3, v1, v3
	v_cmp_ge_u32_e32 vcc, v3, v0
	v_add_u32_e32 v4, 1, v2
	v_add_u32_e32 v1, 1, v1
	v_cndmask_b32_e32 v2, v2, v4, vcc
	v_sub_u32_e32 v4, v3, v0
	v_cndmask_b32_e32 v3, v3, v4, vcc
	v_cmp_ge_u32_e32 vcc, v3, v0
	v_add_u32_e32 v3, 1, v2
	s_nop 0
	v_cndmask_b32_e32 v2, v2, v3, vcc
	v_mul_lo_u32 v3, v0, v2
	v_add_u32_e32 v0, v3, v0
	v_cmp_ne_u32_e32 vcc, v1, v0
	v_mov_b32_e32 v2, v0
	s_and_saveexec_b64 s[2:3], vcc
	s_cbranch_execz .LBB0_1623
	v_readlane_b32 s4, v254, 25
	v_mov_b32_e32 v0, 0
	v_readlane_b32 s5, v254, 26
	s_mov_b64 s[6:7], 0
	s_nop 3
	global_load_dword v1, v0, s[4:5] sc1
	s_waitcnt vmcnt(0)
	v_cmp_lt_u32_e32 vcc, v1, v2
	s_and_saveexec_b64 s[4:5], vcc
	s_cbranch_execz .LBB0_1622
	s_mov_b64 s[24:25], s[10:11]
	s_mov_b32 s16, 1
	s_branch .LBB0_1615

.LBB0_1619:
	v_readlane_b32 s10, v254, 25
	v_readlane_b32 s11, v254, 26
	s_add_i32 s16, s16, 1
	s_nop 3
	global_load_dword v1, v0, s[10:11] sc1
	s_mov_b64 s[10:11], -1
	s_waitcnt vmcnt(0)
	v_cmp_ge_u32_e32 vcc, v1, v2
	s_orn2_b64 s[14:15], vcc, exec
	s_branch .LBB0_1614

.LBB0_1675:
	s_or_b64 exec, exec, s[2:3]
	v_cvt_f32_u32_e32 v4, v2
	s_waitcnt vmcnt(0)
	v_readfirstlane_b32 s2, v3
	v_sub_u32_e32 v3, 0, v2
	v_rcp_iflag_f32_e32 v4, v4
	v_add_u32_e32 v5, s2, v1
	v_mul_f32_e32 v4, 0x4f7ffffe, v4
	v_cvt_u32_f32_e32 v4, v4
	v_mul_lo_u32 v1, v3, v4
	v_mul_hi_u32 v1, v4, v1
	v_add_u32_e32 v1, v4, v1
	v_mul_hi_u32 v1, v5, v1
	v_mul_lo_u32 v3, v1, v2
	v_sub_u32_e32 v3, v5, v3
	v_add_u32_e32 v4, 1, v1
	v_cmp_ge_u32_e32 vcc, v3, v2
	s_nop 1
	v_cndmask_b32_e32 v1, v1, v4, vcc
	v_sub_u32_e32 v4, v3, v2
	v_cndmask_b32_e32 v3, v3, v4, vcc
	v_add_u32_e32 v4, 1, v1
	v_cmp_ge_u32_e32 vcc, v3, v2
	v_add_u32_e32 v3, 1, v5
	s_nop 0
	v_cndmask_b32_e32 v1, v1, v4, vcc
	v_mul_lo_u32 v4, v2, v1
	v_add_u32_e32 v2, v4, v2
	v_cmp_ne_u32_e32 vcc, v3, v2
	s_and_saveexec_b64 s[2:3], vcc
	s_xor_b64 s[2:3], exec, s[2:3]
	s_cbranch_execz .LBB0_1689
	v_readlane_b32 s4, v254, 29
	s_waitcnt lgkmcnt(0)
	v_add_u32_e32 v1, 1, v1
	v_mul_lo_u32 v1, v1, v0
	v_mov_b32_e32 v0, 0
	v_readlane_b32 s5, v254, 30
	s_nop 4
	global_load_dword v2, v0, s[4:5] sc1
	s_waitcnt vmcnt(0)
	v_cmp_lt_u32_e32 vcc, v2, v1
	s_and_saveexec_b64 s[4:5], vcc
	s_cbranch_execz .LBB0_1688
	s_mov_b32 s16, 1
	s_mov_b64 s[6:7], 0
	s_branch .LBB0_1679

.LBB0_1692:
	s_or_b64 exec, exec, s[4:5]
	v_cvt_f32_u32_e32 v3, v0
	s_waitcnt vmcnt(0)
	v_readfirstlane_b32 s2, v2
	v_readlane_b32 s18, v254, 25
	v_readlane_b32 s19, v254, 26
	v_rcp_iflag_f32_e32 v3, v3
	v_add_u32_e32 v1, s2, v1
	v_add_u32_e32 v4, 1, v1
	s_mov_b64 s[4:5], 0
	v_mul_f32_e32 v2, 0x4f7ffffe, v3
	v_cvt_u32_f32_e32 v2, v2
	v_sub_u32_e32 v3, 0, v0
	v_mul_lo_u32 v3, v3, v2
	v_mul_hi_u32 v3, v2, v3
	v_add_u32_e32 v2, v2, v3
	v_mul_hi_u32 v2, v1, v2
	v_mul_lo_u32 v3, v2, v0
	v_sub_u32_e32 v1, v1, v3
	v_add_u32_e32 v5, 1, v2
	v_cmp_ge_u32_e32 vcc, v1, v0
	v_sub_u32_e32 v3, v1, v0
	s_nop 0
	v_cndmask_b32_e32 v2, v2, v5, vcc
	v_cndmask_b32_e32 v1, v1, v3, vcc
	v_add_u32_e32 v3, 1, v2
	v_cmp_ge_u32_e32 vcc, v1, v0
	s_nop 1
	v_cndmask_b32_e32 v2, v2, v3, vcc
	v_mul_lo_u32 v1, v0, v2
	v_add_u32_e32 v0, v1, v0
	v_cmp_ne_u32_e32 vcc, v4, v0
	v_mov_b32_e32 v2, v0
	s_and_saveexec_b64 s[2:3], vcc
	s_cbranch_execz .LBB0_1704
	v_mov_b32_e32 v0, 0
	global_load_dword v1, v0, s[18:19] sc1
	s_mov_b64 s[6:7], 0
	s_waitcnt vmcnt(0)
	v_cmp_lt_u32_e32 vcc, v1, v2
	s_and_saveexec_b64 s[4:5], vcc
	s_cbranch_execz .LBB0_1703
	s_mov_b32 s16, 1
	s_branch .LBB0_1696

.LBB0_1700:
	global_load_dword v1, v0, s[18:19] sc1
	s_add_i32 s16, s16, 1
	s_mov_b64 s[10:11], -1
	s_waitcnt vmcnt(0)
	v_cmp_ge_u32_e32 vcc, v1, v2
	s_orn2_b64 s[14:15], vcc, exec
	s_branch .LBB0_1695
